# RG-LRU task prologue: the first load group (conv weights, first gate-weight unit) no longer waited separately, its conversion joins the first merged group
# speedup vs baseline: 1.0030x; 1.0007x over previous
.LBB0_200:
	s_or_b64 exec, exec, s[80:81]
	v_readfirstlane_b32 s1, v0
	s_cmpk_gt_u32 s1, 0xff
	s_mov_b64 s[80:81], -1
	s_cbranch_scc1 .LBB0_195
	s_and_b32 s0, s45, 7
	s_lshl_b32 s0, s0, 8
	s_or_b32 s1, s1, s0
	s_bfe_u32 s0, s1, 0x30005
	s_lshl_b32 s20, s0, 8
	v_lshl_add_u64 v[24:25], v[144:145], 0, s[20:21]
	v_lshl_add_u64 v[20:21], v[146:147], 0, s[20:21]
	s_lshl_b32 s20, s0, 14
	v_lshl_add_u64 v[44:45], v[148:149], 0, s[20:21]
	v_mov_b32_e32 v161, v99
	v_lshl_add_u64 v[68:69], v[44:45], 0, v[160:161]
	global_load_dword v40, v[68:69], off offset:256
	global_load_dword v233, v[68:69], off
	global_load_dwordx4 v[0:3], v[24:25], off offset:16
	global_load_dwordx4 v[4:7], v[24:25], off
	global_load_dwordx4 v[8:11], v[24:25], off offset:2064
	global_load_dwordx4 v[12:15], v[24:25], off offset:2048
	v_add_co_u32_e32 v32, vcc, 0x1000, v24
	s_mov_b64 s[22:23], 0x1800
	v_lshl_add_u64 v[28:29], v[24:25], 0, s[54:55]
	v_lshl_add_u64 v[36:37], v[24:25], 0, s[22:23]
	v_addc_co_u32_e32 v33, vcc, 0, v25, vcc
	global_load_dwordx4 v[16:19], v[20:21], off offset:16
	s_nop 0
	global_load_dwordx4 v[20:23], v[20:21], off
	s_nop 0
	global_load_dwordx4 v[24:27], v[32:33], off
	s_nop 0
	global_load_dwordx4 v[28:31], v[28:29], off offset:16
	s_nop 0
	global_load_dwordx4 v[32:35], v[32:33], off offset:2048
	s_nop 0
	global_load_dwordx4 v[36:39], v[36:37], off offset:16
	v_mov_b32_e32 v163, v99
	v_lshl_add_u64 v[72:73], v[44:45], 0, v[162:163]
	v_lshl_add_u64 v[76:77], v[150:151], 0, s[20:21]
	v_lshl_add_u64 v[104:105], v[76:77], 0, v[160:161]
	v_lshl_add_u64 v[108:109], v[76:77], 0, v[162:163]
	s_lshl_b32 s26, s0, 6
	s_lshr_b32 s23, s1, 8
	s_lshl_b32 s1, s1, 7
	s_and_b32 s22, s1, 0xf80
	s_lshl_b32 s1, s23, 12
	s_or_b32 s20, s22, s1
	s_add_u32 s80, s20, -3
	s_addc_u32 s81, 0, -1
	v_cmp_gt_i32_e32 vcc, s22, v172
	v_mov_b32_e32 v110, v99
	v_mov_b32_e32 v111, v99
	global_load_dword v41, v[68:69], off offset:768
	global_load_dword v234, v[68:69], off offset:512
	global_load_dword v42, v[68:69], off offset:1280
	global_load_dword v235, v[68:69], off offset:1024
	global_load_dword v43, v[68:69], off offset:1792
	global_load_dword v236, v[68:69], off offset:1536
	global_load_dword v44, v[72:73], off offset:256
	global_load_dword v237, v[72:73], off
	global_load_dword v45, v[72:73], off offset:768
	global_load_dword v238, v[72:73], off offset:512
	global_load_dword v46, v[72:73], off offset:1280
	global_load_dword v239, v[72:73], off offset:1024
	global_load_dword v47, v[72:73], off offset:1792
	global_load_dword v240, v[72:73], off offset:1536
	global_load_dword v48, v[68:69], off offset:320
	global_load_dword v241, v[68:69], off offset:64
	global_load_dword v49, v[68:69], off offset:832
	global_load_dword v242, v[68:69], off offset:576
	global_load_dword v50, v[68:69], off offset:1344
	global_load_dword v243, v[68:69], off offset:1088
	global_load_dword v51, v[68:69], off offset:1856
	global_load_dword v244, v[68:69], off offset:1600
	global_load_dword v52, v[72:73], off offset:320
	global_load_dword v245, v[72:73], off offset:64
	global_load_dword v53, v[72:73], off offset:832
	global_load_dword v246, v[72:73], off offset:576
	global_load_dword v54, v[72:73], off offset:1344
	global_load_dword v247, v[72:73], off offset:1088
	global_load_dword v55, v[72:73], off offset:1856
	global_load_dword v248, v[72:73], off offset:1600
	global_load_dword v56, v[68:69], off offset:384
	global_load_dword v249, v[68:69], off offset:128
	global_load_dword v57, v[68:69], off offset:896
	global_load_dword v250, v[68:69], off offset:640
	global_load_dword v58, v[68:69], off offset:1408
	global_load_dword v251, v[68:69], off offset:1152
	global_load_dword v59, v[68:69], off offset:1920
	global_load_dword v252, v[68:69], off offset:1664
	global_load_dword v60, v[72:73], off offset:384
	global_load_dword v253, v[72:73], off offset:128
	global_load_dword v61, v[72:73], off offset:896
	global_load_dword v135, v[72:73], off offset:640
	global_load_dword v62, v[72:73], off offset:1408
	global_load_dword v136, v[72:73], off offset:1152
	global_load_dword v63, v[72:73], off offset:1920
	global_load_dword v137, v[72:73], off offset:1664
	global_load_dword v64, v[68:69], off offset:448
	global_load_dword v138, v[68:69], off offset:192
	global_load_dword v65, v[68:69], off offset:960
	global_load_dword v139, v[68:69], off offset:704
	global_load_dword v66, v[68:69], off offset:1472
	global_load_dword v140, v[68:69], off offset:1216
	global_load_dword v67, v[68:69], off offset:1984
	s_nop 0
	global_load_dword v141, v[68:69], off offset:1728
	global_load_dword v68, v[72:73], off offset:448
	global_load_dword v142, v[72:73], off offset:192
	global_load_dword v69, v[72:73], off offset:960
	global_load_dword v143, v[72:73], off offset:704
	global_load_dword v70, v[72:73], off offset:1472
	global_load_dword v165, v[72:73], off offset:1216
	global_load_dword v71, v[72:73], off offset:1984
	s_nop 0
	global_load_dword v168, v[72:73], off offset:1728
	global_load_dword v72, v[104:105], off offset:256
	global_load_dword v170, v[104:105], off
	global_load_dword v73, v[104:105], off offset:768
	global_load_dword v171, v[104:105], off offset:512
	global_load_dword v74, v[104:105], off offset:1280
	global_load_dword v222, v[104:105], off offset:1024
	global_load_dword v75, v[104:105], off offset:1792
	global_load_dword v223, v[104:105], off offset:1536
	global_load_dword v76, v[108:109], off offset:256
	global_load_dword v224, v[108:109], off
	global_load_dword v77, v[108:109], off offset:768
	global_load_dword v225, v[108:109], off offset:512
	global_load_dword v78, v[108:109], off offset:1280
	global_load_dword v226, v[108:109], off offset:1024
	global_load_dword v79, v[108:109], off offset:1792
	global_load_dword v227, v[108:109], off offset:1536
	global_load_dword v80, v[104:105], off offset:320
	global_load_dword v228, v[104:105], off offset:64
	s_waitcnt vmcnt(0)
	v_cvt_pk_bf16_f32 v40, v233, v40
	v_cvt_pk_bf16_f32 v41, v234, v41
	v_cvt_pk_bf16_f32 v42, v235, v42
	v_cvt_pk_bf16_f32 v43, v236, v43
	v_cvt_pk_bf16_f32 v44, v237, v44
	v_cvt_pk_bf16_f32 v45, v238, v45
	v_cvt_pk_bf16_f32 v46, v239, v46
	v_cvt_pk_bf16_f32 v47, v240, v47
	v_cvt_pk_bf16_f32 v48, v241, v48
	v_cvt_pk_bf16_f32 v49, v242, v49
	v_cvt_pk_bf16_f32 v50, v243, v50
	v_cvt_pk_bf16_f32 v51, v244, v51
	v_cvt_pk_bf16_f32 v52, v245, v52
	v_cvt_pk_bf16_f32 v53, v246, v53
	v_cvt_pk_bf16_f32 v54, v247, v54
	v_cvt_pk_bf16_f32 v55, v248, v55
	v_cvt_pk_bf16_f32 v56, v249, v56
	v_cvt_pk_bf16_f32 v57, v250, v57
	v_cvt_pk_bf16_f32 v58, v251, v58
	v_cvt_pk_bf16_f32 v59, v252, v59
	v_cvt_pk_bf16_f32 v60, v253, v60
	v_cvt_pk_bf16_f32 v61, v135, v61
	v_cvt_pk_bf16_f32 v62, v136, v62
	v_cvt_pk_bf16_f32 v63, v137, v63
	v_cvt_pk_bf16_f32 v64, v138, v64
	v_cvt_pk_bf16_f32 v65, v139, v65
	v_cvt_pk_bf16_f32 v66, v140, v66
	v_cvt_pk_bf16_f32 v67, v141, v67
	v_cvt_pk_bf16_f32 v68, v142, v68
	v_cvt_pk_bf16_f32 v69, v143, v69
	v_cvt_pk_bf16_f32 v70, v165, v70
	v_cvt_pk_bf16_f32 v71, v168, v71
	v_cvt_pk_bf16_f32 v72, v170, v72
	v_cvt_pk_bf16_f32 v73, v171, v73
	v_cvt_pk_bf16_f32 v74, v222, v74
	v_cvt_pk_bf16_f32 v75, v223, v75
	v_cvt_pk_bf16_f32 v76, v224, v76
	v_cvt_pk_bf16_f32 v77, v225, v77
	v_cvt_pk_bf16_f32 v78, v226, v78
	v_cvt_pk_bf16_f32 v79, v227, v79
	v_cvt_pk_bf16_f32 v80, v228, v80
	global_load_dword v81, v[104:105], off offset:832
	global_load_dword v234, v[104:105], off offset:576
	global_load_dword v82, v[104:105], off offset:1344
	global_load_dword v235, v[104:105], off offset:1088
	global_load_dword v83, v[104:105], off offset:1856
	global_load_dword v236, v[104:105], off offset:1600
	global_load_dword v84, v[108:109], off offset:320
	global_load_dword v237, v[108:109], off offset:64
	global_load_dword v85, v[108:109], off offset:832
	global_load_dword v238, v[108:109], off offset:576
	global_load_dword v86, v[108:109], off offset:1344
	global_load_dword v239, v[108:109], off offset:1088
	global_load_dword v87, v[108:109], off offset:1856
	global_load_dword v240, v[108:109], off offset:1600
	global_load_dword v88, v[104:105], off offset:384
	global_load_dword v241, v[104:105], off offset:128
	global_load_dword v89, v[104:105], off offset:896
	global_load_dword v242, v[104:105], off offset:640
	global_load_dword v90, v[104:105], off offset:1408
	global_load_dword v243, v[104:105], off offset:1152
	global_load_dword v91, v[104:105], off offset:1920
	global_load_dword v244, v[104:105], off offset:1664
	global_load_dword v92, v[108:109], off offset:384
	global_load_dword v245, v[108:109], off offset:128
	global_load_dword v93, v[108:109], off offset:896
	global_load_dword v246, v[108:109], off offset:640
	global_load_dword v94, v[108:109], off offset:1408
	global_load_dword v247, v[108:109], off offset:1152
	global_load_dword v95, v[108:109], off offset:1920
	global_load_dword v248, v[108:109], off offset:1664
	global_load_dword v249, v[104:105], off offset:448
	global_load_dword v100, v[104:105], off offset:192
	global_load_dword v250, v[104:105], off offset:960
	global_load_dword v101, v[104:105], off offset:704
	global_load_dword v251, v[104:105], off offset:1472
	global_load_dword v102, v[104:105], off offset:1216
	global_load_dword v252, v[104:105], off offset:1984
	global_load_dword v103, v[104:105], off offset:1728
	global_load_dword v253, v[108:109], off offset:448
	global_load_dword v104, v[108:109], off offset:192
	global_load_dword v135, v[108:109], off offset:960
	global_load_dword v105, v[108:109], off offset:704
	global_load_dword v136, v[108:109], off offset:1472
	global_load_dword v106, v[108:109], off offset:1216
	global_load_dword v137, v[108:109], off offset:1984
	global_load_dword v107, v[108:109], off offset:1728
	v_or_b32_e32 v108, s26, v97
	v_lshlrev_b32_e32 v108, 2, v108
	v_mov_b32_e32 v109, v99
	s_waitcnt vmcnt(0)
	v_cvt_pk_bf16_f32 v81, v234, v81
	v_cvt_pk_bf16_f32 v82, v235, v82
	v_cvt_pk_bf16_f32 v83, v236, v83
	v_cvt_pk_bf16_f32 v84, v237, v84
	v_cvt_pk_bf16_f32 v85, v238, v85
	v_cvt_pk_bf16_f32 v86, v239, v86
	v_cvt_pk_bf16_f32 v87, v240, v87
	v_cvt_pk_bf16_f32 v88, v241, v88
	v_cvt_pk_bf16_f32 v89, v242, v89
	v_cvt_pk_bf16_f32 v90, v243, v90
	v_cvt_pk_bf16_f32 v91, v244, v91
	v_cvt_pk_bf16_f32 v92, v245, v92
	v_cvt_pk_bf16_f32 v93, v246, v93
	v_cvt_pk_bf16_f32 v94, v247, v94
	v_cvt_pk_bf16_f32 v95, v248, v95
	v_cvt_pk_bf16_f32 v100, v100, v249
	v_cvt_pk_bf16_f32 v101, v101, v250
	v_cvt_pk_bf16_f32 v102, v102, v251
	v_cvt_pk_bf16_f32 v103, v103, v252
	v_cvt_pk_bf16_f32 v104, v104, v253
	v_cvt_pk_bf16_f32 v105, v105, v135
	v_cvt_pk_bf16_f32 v106, v106, v136
	v_cvt_pk_bf16_f32 v107, v107, v137
	global_load_dword v161, v108, s[74:75]
	global_load_dword v163, v108, s[76:77]
	global_load_dword v181, v108, s[74:75] offset:64
	global_load_dword v188, v108, s[76:77] offset:64
	global_load_dword v189, v108, s[74:75] offset:128
	global_load_dword v190, v108, s[76:77] offset:128
	global_load_dword v191, v108, s[76:77] offset:192
	global_load_dword v192, v108, s[74:75] offset:192
	global_load_dword v123, v108, s[78:79]
	global_load_dword v122, v108, s[78:79] offset:64
	global_load_dword v121, v108, s[78:79] offset:128
	global_load_dword v120, v108, s[78:79] offset:192
	v_mov_b32_e32 v108, v99
	v_lshlrev_b32_e32 v98, 1, v96
	s_and_saveexec_b64 s[82:83], vcc
	s_cbranch_execz .LBB0_203
	v_lshl_add_u64 v[108:109], s[80:81], 0, v[152:153]
	v_mov_b64_e32 v[110:111], s[16:17]
	v_mad_u64_u32 v[110:111], s[42:43], v108, s99, v[110:111]
	v_mad_i32_i24 v111, v109, s99, v111
	s_lshl_b32 s20, s26, 1
	v_lshl_add_u64 v[108:109], v[110:111], 0, s[20:21]
	v_lshl_add_u64 v[108:109], v[108:109], 0, v[98:99]
	global_load_dwordx4 v[108:111], v[108:109], off offset:3072

.LBB0_250:
	s_bfe_u32 s0, s23, 0x30005
	s_lshl_b32 s20, s0, 8
	v_lshl_add_u64 v[24:25], v[96:97], 0, s[20:21]
	v_lshl_add_u64 v[20:21], v[152:153], 0, s[20:21]
	s_lshl_b32 s20, s0, 14
	v_lshl_add_u64 v[44:45], v[154:155], 0, s[20:21]
	v_mov_b32_e32 v173, v99
	v_lshl_add_u64 v[68:69], v[44:45], 0, v[172:173]
	global_load_dword v40, v[68:69], off offset:256
	global_load_dword v251, v[68:69], off
	global_load_dwordx4 v[0:3], v[24:25], off offset:16
	global_load_dwordx4 v[4:7], v[24:25], off
	global_load_dwordx4 v[8:11], v[24:25], off offset:2064
	global_load_dwordx4 v[12:15], v[24:25], off offset:2048
	v_add_co_u32_e32 v32, vcc, 0x1000, v24
	s_mov_b64 s[26:27], 0x1800
	v_lshl_add_u64 v[28:29], v[24:25], 0, s[54:55]
	v_lshl_add_u64 v[36:37], v[24:25], 0, s[26:27]
	v_addc_co_u32_e32 v33, vcc, 0, v25, vcc
	global_load_dwordx4 v[16:19], v[20:21], off offset:16
	s_nop 0
	global_load_dwordx4 v[20:23], v[20:21], off
	s_nop 0
	global_load_dwordx4 v[24:27], v[32:33], off
	s_nop 0
	global_load_dwordx4 v[28:31], v[28:29], off offset:16
	s_nop 0
	global_load_dwordx4 v[32:35], v[32:33], off offset:2048
	s_nop 0
	global_load_dwordx4 v[36:39], v[36:37], off offset:16
	v_mov_b32_e32 v175, v99
	v_lshl_add_u64 v[72:73], v[44:45], 0, v[174:175]
	v_lshl_add_u64 v[76:77], v[156:157], 0, s[20:21]
	v_lshl_add_u64 v[104:105], v[76:77], 0, v[172:173]
	v_lshl_add_u64 v[108:109], v[76:77], 0, v[174:175]
	s_lshl_b32 s1, s0, 6
	s_lshr_b32 s0, s23, 5
	s_ashr_i32 s72, s23, 8
	s_and_b32 s20, s23, 31
	s_cmp_eq_u32 s20, 0
	global_load_dword v41, v[68:69], off offset:768
	global_load_dword v252, v[68:69], off offset:512
	global_load_dword v42, v[68:69], off offset:1280
	global_load_dword v253, v[68:69], off offset:1024
	global_load_dword v43, v[68:69], off offset:1792
	global_load_dword v230, v[68:69], off offset:1536
	global_load_dword v44, v[72:73], off offset:256
	global_load_dword v231, v[72:73], off
	global_load_dword v45, v[72:73], off offset:768
	global_load_dword v232, v[72:73], off offset:512
	global_load_dword v46, v[72:73], off offset:1280
	global_load_dword v233, v[72:73], off offset:1024
	global_load_dword v47, v[72:73], off offset:1792
	global_load_dword v234, v[72:73], off offset:1536
	global_load_dword v48, v[68:69], off offset:320
	global_load_dword v235, v[68:69], off offset:64
	global_load_dword v49, v[68:69], off offset:832
	global_load_dword v120, v[68:69], off offset:576
	global_load_dword v50, v[68:69], off offset:1344
	global_load_dword v121, v[68:69], off offset:1088
	global_load_dword v51, v[68:69], off offset:1856
	global_load_dword v122, v[68:69], off offset:1600
	global_load_dword v52, v[72:73], off offset:320
	global_load_dword v123, v[72:73], off offset:64
	global_load_dword v53, v[72:73], off offset:832
	global_load_dword v143, v[72:73], off offset:576
	global_load_dword v54, v[72:73], off offset:1344
	global_load_dword v144, v[72:73], off offset:1088
	global_load_dword v55, v[72:73], off offset:1856
	global_load_dword v137, v[72:73], off offset:1600
	global_load_dword v56, v[68:69], off offset:384
	global_load_dword v138, v[68:69], off offset:128
	global_load_dword v57, v[68:69], off offset:896
	global_load_dword v139, v[68:69], off offset:640
	global_load_dword v58, v[68:69], off offset:1408
	global_load_dword v140, v[68:69], off offset:1152
	global_load_dword v59, v[68:69], off offset:1920
	global_load_dword v141, v[68:69], off offset:1664
	global_load_dword v60, v[72:73], off offset:384
	global_load_dword v142, v[72:73], off offset:128
	global_load_dword v61, v[72:73], off offset:896
	global_load_dword v133, v[72:73], off offset:640
	global_load_dword v62, v[72:73], off offset:1408
	global_load_dword v134, v[72:73], off offset:1152
	global_load_dword v63, v[72:73], off offset:1920
	global_load_dword v135, v[72:73], off offset:1664
	global_load_dword v64, v[68:69], off offset:448
	global_load_dword v136, v[68:69], off offset:192
	global_load_dword v65, v[68:69], off offset:960
	global_load_dword v239, v[68:69], off offset:704
	global_load_dword v66, v[68:69], off offset:1472
	global_load_dword v240, v[68:69], off offset:1216
	global_load_dword v67, v[68:69], off offset:1984
	s_nop 0
	global_load_dword v149, v[68:69], off offset:1728
	global_load_dword v68, v[72:73], off offset:448
	global_load_dword v150, v[72:73], off offset:192
	global_load_dword v69, v[72:73], off offset:960
	global_load_dword v151, v[72:73], off offset:704
	global_load_dword v70, v[72:73], off offset:1472
	global_load_dword v236, v[72:73], off offset:1216
	global_load_dword v71, v[72:73], off offset:1984
	s_nop 0
	global_load_dword v237, v[72:73], off offset:1728
	global_load_dword v72, v[104:105], off offset:256
	global_load_dword v238, v[104:105], off
	global_load_dword v73, v[104:105], off offset:768
	global_load_dword v145, v[104:105], off offset:512
	global_load_dword v74, v[104:105], off offset:1280
	global_load_dword v146, v[104:105], off offset:1024
	global_load_dword v75, v[104:105], off offset:1792
	global_load_dword v147, v[104:105], off offset:1536
	global_load_dword v76, v[108:109], off offset:256
	global_load_dword v148, v[108:109], off
	s_waitcnt vmcnt(0)
	v_cvt_pk_bf16_f32 v40, v251, v40
	v_cvt_pk_bf16_f32 v41, v252, v41
	v_cvt_pk_bf16_f32 v42, v253, v42
	v_cvt_pk_bf16_f32 v43, v230, v43
	v_cvt_pk_bf16_f32 v44, v231, v44
	v_cvt_pk_bf16_f32 v45, v232, v45
	v_cvt_pk_bf16_f32 v46, v233, v46
	v_cvt_pk_bf16_f32 v47, v234, v47
	v_cvt_pk_bf16_f32 v48, v235, v48
	v_cvt_pk_bf16_f32 v49, v120, v49
	v_cvt_pk_bf16_f32 v50, v121, v50
	v_cvt_pk_bf16_f32 v51, v122, v51
	v_cvt_pk_bf16_f32 v52, v123, v52
	v_cvt_pk_bf16_f32 v53, v143, v53
	v_cvt_pk_bf16_f32 v54, v144, v54
	v_cvt_pk_bf16_f32 v55, v137, v55
	v_cvt_pk_bf16_f32 v56, v138, v56
	v_cvt_pk_bf16_f32 v57, v139, v57
	v_cvt_pk_bf16_f32 v58, v140, v58
	v_cvt_pk_bf16_f32 v59, v141, v59
	v_cvt_pk_bf16_f32 v60, v142, v60
	v_cvt_pk_bf16_f32 v61, v133, v61
	v_cvt_pk_bf16_f32 v62, v134, v62
	v_cvt_pk_bf16_f32 v63, v135, v63
	v_cvt_pk_bf16_f32 v64, v136, v64
	v_cvt_pk_bf16_f32 v65, v239, v65
	v_cvt_pk_bf16_f32 v66, v240, v66
	v_cvt_pk_bf16_f32 v67, v149, v67
	v_cvt_pk_bf16_f32 v68, v150, v68
	v_cvt_pk_bf16_f32 v69, v151, v69
	v_cvt_pk_bf16_f32 v70, v236, v70
	v_cvt_pk_bf16_f32 v71, v237, v71
	v_cvt_pk_bf16_f32 v72, v238, v72
	v_cvt_pk_bf16_f32 v73, v145, v73
	v_cvt_pk_bf16_f32 v74, v146, v74
	v_cvt_pk_bf16_f32 v75, v147, v75
	v_cvt_pk_bf16_f32 v76, v148, v76
	global_load_dword v77, v[108:109], off offset:768
	global_load_dword v252, v[108:109], off offset:512
	global_load_dword v78, v[108:109], off offset:1280
	global_load_dword v253, v[108:109], off offset:1024
	global_load_dword v79, v[108:109], off offset:1792
	global_load_dword v230, v[108:109], off offset:1536
	global_load_dword v80, v[104:105], off offset:320
	global_load_dword v231, v[104:105], off offset:64
	global_load_dword v81, v[104:105], off offset:832
	global_load_dword v232, v[104:105], off offset:576
	global_load_dword v82, v[104:105], off offset:1344
	global_load_dword v233, v[104:105], off offset:1088
	global_load_dword v83, v[104:105], off offset:1856
	global_load_dword v234, v[104:105], off offset:1600
	global_load_dword v84, v[108:109], off offset:320
	global_load_dword v235, v[108:109], off offset:64
	global_load_dword v85, v[108:109], off offset:832
	global_load_dword v120, v[108:109], off offset:576
	global_load_dword v86, v[108:109], off offset:1344
	global_load_dword v121, v[108:109], off offset:1088
	global_load_dword v87, v[108:109], off offset:1856
	global_load_dword v122, v[108:109], off offset:1600
	global_load_dword v88, v[104:105], off offset:384
	global_load_dword v123, v[104:105], off offset:128
	global_load_dword v89, v[104:105], off offset:896
	global_load_dword v143, v[104:105], off offset:640
	global_load_dword v90, v[104:105], off offset:1408
	global_load_dword v144, v[104:105], off offset:1152
	global_load_dword v91, v[104:105], off offset:1920
	global_load_dword v137, v[104:105], off offset:1664
	global_load_dword v92, v[108:109], off offset:384
	global_load_dword v138, v[108:109], off offset:128
	global_load_dword v93, v[108:109], off offset:896
	global_load_dword v139, v[108:109], off offset:640
	global_load_dword v94, v[108:109], off offset:1408
	global_load_dword v140, v[108:109], off offset:1152
	global_load_dword v95, v[108:109], off offset:1920
	global_load_dword v141, v[108:109], off offset:1664
	global_load_dword v100, v[104:105], off offset:448
	global_load_dword v142, v[104:105], off offset:192
	global_load_dword v101, v[104:105], off offset:960
	global_load_dword v133, v[104:105], off offset:704
	global_load_dword v102, v[104:105], off offset:1472
	global_load_dword v134, v[104:105], off offset:1216
	global_load_dword v103, v[104:105], off offset:1984
	s_nop 0
	global_load_dword v135, v[104:105], off offset:1728
	global_load_dword v104, v[108:109], off offset:448
	global_load_dword v136, v[108:109], off offset:192
	global_load_dword v105, v[108:109], off offset:960
	global_load_dword v146, v[108:109], off offset:704
	global_load_dword v106, v[108:109], off offset:1472
	global_load_dword v147, v[108:109], off offset:1216
	global_load_dword v107, v[108:109], off offset:1984
	s_nop 0
	global_load_dword v145, v[108:109], off offset:1728
	v_or_b32_e32 v109, s1, v220
	v_lshlrev_b32_e32 v109, 2, v109
	s_waitcnt vmcnt(0)
	v_cvt_pk_bf16_f32 v77, v252, v77
	v_cvt_pk_bf16_f32 v78, v253, v78
	v_cvt_pk_bf16_f32 v79, v230, v79
	v_cvt_pk_bf16_f32 v80, v231, v80
	v_cvt_pk_bf16_f32 v81, v232, v81
	v_cvt_pk_bf16_f32 v82, v233, v82
	v_cvt_pk_bf16_f32 v83, v234, v83
	v_cvt_pk_bf16_f32 v84, v235, v84
	v_cvt_pk_bf16_f32 v85, v120, v85
	v_cvt_pk_bf16_f32 v86, v121, v86
	v_cvt_pk_bf16_f32 v87, v122, v87
	v_cvt_pk_bf16_f32 v88, v123, v88
	v_cvt_pk_bf16_f32 v89, v143, v89
	v_cvt_pk_bf16_f32 v90, v144, v90
	v_cvt_pk_bf16_f32 v91, v137, v91
	v_cvt_pk_bf16_f32 v92, v138, v92
	v_cvt_pk_bf16_f32 v93, v139, v93
	v_cvt_pk_bf16_f32 v94, v140, v94
	v_cvt_pk_bf16_f32 v95, v141, v95
	v_cvt_pk_bf16_f32 v100, v142, v100
	v_cvt_pk_bf16_f32 v101, v133, v101
	v_cvt_pk_bf16_f32 v102, v134, v102
	v_cvt_pk_bf16_f32 v103, v135, v103
	v_cvt_pk_bf16_f32 v104, v136, v104
	v_cvt_pk_bf16_f32 v105, v146, v105
	v_cvt_pk_bf16_f32 v106, v147, v106
	v_cvt_pk_bf16_f32 v107, v145, v107
	global_load_dword v173, v109, s[8:9]
	global_load_dword v175, v109, s[68:69]
	global_load_dword v230, v109, s[8:9] offset:64
	global_load_dword v231, v109, s[68:69] offset:64
	global_load_dword v232, v109, s[8:9] offset:128
	global_load_dword v233, v109, s[68:69] offset:128
	global_load_dword v234, v109, s[68:69] offset:192
	global_load_dword v235, v109, s[8:9] offset:192
	global_load_dword v123, v109, s[70:71]
	global_load_dword v122, v109, s[70:71] offset:64
	global_load_dword v121, v109, s[70:71] offset:128
	global_load_dword v120, v109, s[70:71] offset:192
	s_cbranch_scc1 .LBB0_267
	s_and_b32 s26, s0, 7
	s_lshl_b32 s27, s72, 3
	s_or_b32 s26, s27, s26
	s_ashr_i32 s27, s26, 31
	s_lshl_b64 s[26:27], s[26:27], 14
	v_lshl_add_u64 v[108:109], v[164:165], 0, s[26:27]
	s_mov_b32 s26, 0
	v_mov_b32_e32 v177, 0
	s_branch .LBB0_253
